# up GEMM val tiles stored with nt (gate stays cache-resident for ffn_conv)
# baseline (speedup 1.0000x reference)
; #define PG8_STAGE(bufoff, gbase, voff) do { _Pragma("unroll") for (int _i = 0; _i < 2; ++_i) \
;         __builtin_amdgcn_global_load_lds((const unsigned*)((const char*)(gbase) + (voff)[_i]), (LAS unsigned*)(lds + (bufoff) + ldsw + _i * 8192), 16, 0, 0); } while (0)
; #define PG8_LDA(dst, b, h) do { _Pragma("unroll") for (int m = 0; m < 4; ++m) _Pragma("unroll") for (int k = 0; k < 2; ++k) dst[m][k] = *(const LAS bf16x8*)(lds + PG8_SA(b, h) + aoff + m * 2048 + k * 1024); } while (0)
; #define PG8_LDB(dst, b, h) do { _Pragma("unroll") for (int n = 0; n < 2; ++n) _Pragma("unroll") for (int k = 0; k < 2; ++k) dst[n][k] = *(const LAS bf16x8*)(lds + PG8_SB(b, h) + boff + n * 2048 + k * 1024); } while (0)
; #define PG8_MMA(ai, bj, At, Bt) do { __builtin_amdgcn_s_setprio(1); _Pragma("unroll") for (int m = 0; m < 4; ++m) _Pragma("unroll") for (int n = 0; n < 2; ++n) _Pragma("unroll") for (int k = 0; k < 2; ++k) \
;         acc[ai][bj][m][n] = __builtin_amdgcn_mfma_f32_16x16x32_bf16(Bt[n][k], At[m][k], acc[ai][bj][m][n], 0, 0, 0); __builtin_amdgcn_s_setprio(0); } while (0)
; #define PG8_WAIT_V(n) asm volatile("s_waitcnt vmcnt(" #n ")" ::: "memory")
; #define PG8_WAIT_L(n) asm volatile("s_waitcnt lgkmcnt(" #n ")" ::: "memory")
; #define PG8_BAR __builtin_amdgcn_s_barrier()
; #define PG8_SCHED __builtin_amdgcn_sched_barrier(0)
; template <class Epi, class Sched, bool ALIGN_EPI>
; __device__ __forceinline__ void gemm_phase(LAS unsigned char* lds, const int wid, const int lda_, const int ldb_, const int K_, const Sched& S, const Epi& E) {
;     ...
;             PG8_LDB(B0, 1, 0); PG8_LDB(B1, 1, 1); PG8_SCHED; PG8_LDA(At, 1, 0); PG8_STAGE(PG8_SA(0, 1), a2 + hstepA, voffA);
;             PG8_WAIT_V(8); PG8_WAIT_L(0); PG8_BAR; PG8_MMA(0, 0, At, B0); PG8_MMA(0, 1, At, B1); PG8_BAR; PG8_SCHED;
;             PG8_LDA(At, 1, 1); PG8_STAGE(PG8_SB(1, 0), b3, voffB); PG8_STAGE(PG8_SB(1, 1), b3 + hstepB, voffB); PG8_STAGE(PG8_SA(1, 0), a3, voffA);
;             PG8_WAIT_V(8); PG8_WAIT_L(0); PG8_BAR; PG8_MMA(1, 0, At, B0); PG8_MMA(1, 1, At, B1); PG8_BAR; PG8_SCHED;
.Lgemm_join_1120:
	s_add_i32 s17, 0, 0x18000
	v_add_u32_e32 v141, s17, v135
	s_add_i32 s27, 0, 0x1c000
	ds_read_b128 v[160:163], v141
	ds_read_b128 v[164:167], v141 offset:1024
	ds_read_b128 v[168:171], v141 offset:2048
	ds_read_b128 v[172:175], v141 offset:3072
	v_add_u32_e32 v141, s27, v135
	ds_read_b128 v[180:183], v141
	ds_read_b128 v[184:187], v141 offset:1024
	ds_read_b128 v[188:191], v141 offset:2048
	ds_read_b128 v[192:195], v141 offset:3072
	s_add_u32 s80, s94, s10
	s_addc_u32 s81, s95, s11
	s_mov_b32 m0, s39
	v_lshl_add_u64 v[248:249], s[80:81], 0, v[132:133]
	ds_read_b128 v[196:199], v139 offset:32768
	ds_read_b128 v[200:203], v139 offset:33792
	ds_read_b128 v[204:207], v139 offset:34816
	ds_read_b128 v[208:211], v139 offset:35840
	ds_read_b128 v[212:215], v139 offset:36864
	ds_read_b128 v[216:219], v139 offset:37888
	ds_read_b128 v[220:223], v139 offset:38912
	ds_read_b128 v[224:227], v139 offset:39936
	global_load_lds_dwordx4 v[248:249], off
	v_lshl_add_u64 v[248:249], s[80:81], 0, v[130:131]
	s_mov_b32 m0, s72
	s_nop 0
	global_load_lds_dwordx4 v[248:249], off
	s_waitcnt vmcnt(8)
	s_waitcnt lgkmcnt(0)
	s_barrier
	s_setprio 1
	s_waitcnt lgkmcnt(0)
	v_mfma_f32_16x16x32_bf16 v[124:127], v[160:163], v[196:199], v[124:127]
	v_mfma_f32_16x16x32_bf16 v[120:123], v[168:171], v[196:199], v[120:123]
	v_mfma_f32_16x16x32_bf16 v[116:119], v[160:163], v[204:207], v[116:119]
	v_mfma_f32_16x16x32_bf16 v[112:115], v[168:171], v[204:207], v[112:115]
	v_mfma_f32_16x16x32_bf16 v[100:103], v[160:163], v[212:215], v[100:103]
	v_mfma_f32_16x16x32_bf16 v[96:99], v[168:171], v[212:215], v[96:99]
	v_mfma_f32_16x16x32_bf16 v[84:87], v[160:163], v[220:223], v[84:87]
	v_mfma_f32_16x16x32_bf16 v[80:83], v[168:171], v[220:223], v[80:83]
	v_mfma_f32_16x16x32_bf16 v[124:127], v[164:167], v[200:203], v[124:127]
	v_mfma_f32_16x16x32_bf16 v[120:123], v[172:175], v[200:203], v[120:123]
	v_mfma_f32_16x16x32_bf16 v[116:119], v[164:167], v[208:211], v[116:119]
	v_mfma_f32_16x16x32_bf16 v[112:115], v[172:175], v[208:211], v[112:115]
	v_mfma_f32_16x16x32_bf16 v[100:103], v[164:167], v[216:219], v[100:103]
	v_mfma_f32_16x16x32_bf16 v[96:99], v[172:175], v[216:219], v[96:99]
	v_mfma_f32_16x16x32_bf16 v[84:87], v[164:167], v[224:227], v[84:87]
	v_mfma_f32_16x16x32_bf16 v[80:83], v[172:175], v[224:227], v[80:83]
	s_setprio 0
	s_setprio 1
	v_mfma_f32_16x16x32_bf16 v[108:111], v[180:183], v[196:199], v[108:111]
	v_mfma_f32_16x16x32_bf16 v[104:107], v[188:191], v[196:199], v[104:107]
	v_mfma_f32_16x16x32_bf16 v[92:95], v[180:183], v[204:207], v[92:95]
	v_mfma_f32_16x16x32_bf16 v[88:91], v[188:191], v[204:207], v[88:91]
	v_mfma_f32_16x16x32_bf16 v[76:79], v[180:183], v[212:215], v[76:79]
	v_mfma_f32_16x16x32_bf16 v[72:75], v[188:191], v[212:215], v[72:75]
	v_mfma_f32_16x16x32_bf16 v[68:71], v[180:183], v[220:223], v[68:71]
	v_mfma_f32_16x16x32_bf16 v[64:67], v[188:191], v[220:223], v[64:67]
	v_mfma_f32_16x16x32_bf16 v[108:111], v[184:187], v[200:203], v[108:111]
	v_mfma_f32_16x16x32_bf16 v[104:107], v[192:195], v[200:203], v[104:107]
	v_mfma_f32_16x16x32_bf16 v[92:95], v[184:187], v[208:211], v[92:95]
	v_mfma_f32_16x16x32_bf16 v[88:91], v[192:195], v[208:211], v[88:91]
	v_mfma_f32_16x16x32_bf16 v[76:79], v[184:187], v[216:219], v[76:79]
	v_mfma_f32_16x16x32_bf16 v[72:75], v[192:195], v[216:219], v[72:75]
	v_mfma_f32_16x16x32_bf16 v[68:71], v[184:187], v[224:227], v[68:71]
	v_mfma_f32_16x16x32_bf16 v[64:67], v[192:195], v[224:227], v[64:67]
	s_setprio 0
	s_barrier
	s_add_i32 s17, s17, s3
	v_lshl_add_u64 v[228:229], v[228:229], 0, s[24:25]
	s_mov_b32 m0, s17
	ds_read_b128 v[196:199], v139 offset:49152
	ds_read_b128 v[200:203], v139 offset:50176
	ds_read_b128 v[204:207], v139 offset:51200
	ds_read_b128 v[208:211], v139 offset:52224
	ds_read_b128 v[212:215], v139 offset:53248
	ds_read_b128 v[216:219], v139 offset:54272
	ds_read_b128 v[220:223], v139 offset:55296
	ds_read_b128 v[224:227], v139 offset:56320
	global_load_lds_dwordx4 v[228:229], off
	v_lshl_add_u64 v[228:229], v[230:231], 0, s[24:25]
	s_add_i32 m0, s17, 0x2000
	s_add_i32 s17, s27, s3
	global_load_lds_dwordx4 v[228:229], off
	v_lshl_add_u64 v[228:229], v[232:233], 0, s[24:25]
	s_mov_b32 m0, s17
	s_nop 0
	global_load_lds_dwordx4 v[228:229], off
	v_lshl_add_u64 v[228:229], v[234:235], 0, s[24:25]
	s_add_i32 m0, s17, 0x2000
	s_nop 0
	global_load_lds_dwordx4 v[228:229], off
	v_lshl_add_u64 v[228:229], v[236:237], 0, s[24:25]
	s_mov_b32 m0, s73
	s_nop 0
	global_load_lds_dwordx4 v[228:229], off
	v_lshl_add_u64 v[228:229], v[246:247], 0, s[24:25]
	s_mov_b32 m0, s74
	s_nop 0
	global_load_lds_dwordx4 v[228:229], off
	s_waitcnt vmcnt(8)
	s_waitcnt lgkmcnt(0)
	s_barrier
; __device__ __forceinline__ unsigned cvt_pk_bf16(float lo, float hi) { const f32x2 v = {lo, hi}; return __builtin_bit_cast(unsigned, __builtin_convertvector(v, bf16x2_t)); }
;     template <class Sched> __device__ __forceinline__ void operator()(const f32x4 (&acc)[2][2][4][2], const Unit& u, const Sched& S, int wr, int wc, int fr, int fq) const {
;     ...
;         if (kind == 0) {
;             bf16_t* base = (bf16_t*)uo;
; #pragma unroll
;             for (int ai = 0; ai < 2; ++ai)
; #pragma unroll
;                 for (int m = 0; m < 4; ++m) { bf16_t* rowp = base + (size_t)(rl0 + ai * HALF + m * 16) * ldo + cl0;
; #pragma unroll
;                     for (int bj = 0; bj < 2; ++bj) { const f32x4 v0 = acc[ai][bj][m][0], v1 = acc[ai][bj][m][1];
;                         u32x4 w; w.x = cvt_pk_bf16(v0[0], v0[1]); w.y = cvt_pk_bf16(v0[2], v0[3]); w.z = cvt_pk_bf16(v1[0], v1[1]); w.w = cvt_pk_bf16(v1[2], v1[3]);
;                         *(u32x4*)(rowp + bj * HALF) = w; } }
	s_setprio 1
	s_waitcnt lgkmcnt(0)
	v_mfma_f32_16x16x32_bf16 v[60:63], v[160:163], v[196:199], v[60:63]
	v_mfma_f32_16x16x32_bf16 v[56:59], v[168:171], v[196:199], v[56:59]
	v_mfma_f32_16x16x32_bf16 v[52:55], v[160:163], v[204:207], v[52:55]
	v_mfma_f32_16x16x32_bf16 v[48:51], v[168:171], v[204:207], v[48:51]
	v_mfma_f32_16x16x32_bf16 v[36:39], v[160:163], v[212:215], v[36:39]
	v_mfma_f32_16x16x32_bf16 v[32:35], v[168:171], v[212:215], v[32:35]
	v_mfma_f32_16x16x32_bf16 v[20:23], v[160:163], v[220:223], v[20:23]
	v_mfma_f32_16x16x32_bf16 v[16:19], v[168:171], v[220:223], v[16:19]
	v_mfma_f32_16x16x32_bf16 v[60:63], v[164:167], v[200:203], v[60:63]
	v_mfma_f32_16x16x32_bf16 v[56:59], v[172:175], v[200:203], v[56:59]
	v_mfma_f32_16x16x32_bf16 v[52:55], v[164:167], v[208:211], v[52:55]
	v_mfma_f32_16x16x32_bf16 v[48:51], v[172:175], v[208:211], v[48:51]
	v_mfma_f32_16x16x32_bf16 v[36:39], v[164:167], v[216:219], v[36:39]
	v_mfma_f32_16x16x32_bf16 v[32:35], v[172:175], v[216:219], v[32:35]
	v_mfma_f32_16x16x32_bf16 v[20:23], v[164:167], v[224:227], v[20:23]
	v_mfma_f32_16x16x32_bf16 v[16:19], v[172:175], v[224:227], v[16:19]
	s_setprio 0
	s_setprio 1
	v_mfma_f32_16x16x32_bf16 v[44:47], v[180:183], v[196:199], v[44:47]
	v_mfma_f32_16x16x32_bf16 v[40:43], v[188:191], v[196:199], v[40:43]
	v_mfma_f32_16x16x32_bf16 v[28:31], v[180:183], v[204:207], v[28:31]
	v_mfma_f32_16x16x32_bf16 v[24:27], v[188:191], v[204:207], v[24:27]
	v_mfma_f32_16x16x32_bf16 v[12:15], v[180:183], v[212:215], v[12:15]
	v_mfma_f32_16x16x32_bf16 v[8:11], v[188:191], v[212:215], v[8:11]
	v_mfma_f32_16x16x32_bf16 v[4:7], v[180:183], v[220:223], v[4:7]
	v_mfma_f32_16x16x32_bf16 v[0:3], v[188:191], v[220:223], v[0:3]
	v_mfma_f32_16x16x32_bf16 v[44:47], v[184:187], v[200:203], v[44:47]
	v_mfma_f32_16x16x32_bf16 v[40:43], v[192:195], v[200:203], v[40:43]
	v_mfma_f32_16x16x32_bf16 v[28:31], v[184:187], v[208:211], v[28:31]
	v_mfma_f32_16x16x32_bf16 v[24:27], v[192:195], v[208:211], v[24:27]
	v_mfma_f32_16x16x32_bf16 v[12:15], v[184:187], v[216:219], v[12:15]
	v_mfma_f32_16x16x32_bf16 v[8:11], v[192:195], v[216:219], v[8:11]
	v_mfma_f32_16x16x32_bf16 v[4:7], v[184:187], v[224:227], v[4:7]
	v_mfma_f32_16x16x32_bf16 v[0:3], v[192:195], v[224:227], v[0:3]
	s_setprio 0
	s_barrier
	s_add_i32 s78, s78, 2
	s_add_u32 s50, s50, 0x100
	s_addc_u32 s51, s51, 0
	s_cmp_gt_u32 s78, 29
	s_cbranch_scc0 .LBB0_1120
	s_setprio 2
	s_sub_i32 s4, s38, 22
	s_ashr_i32 s5, s38, 31
	s_cmp_lt_i32 s38, 22
	s_cselect_b32 s5, s5, 0
	s_cselect_b32 s4, s38, s4
	s_mov_b32 s17, 0x2bc00000
	s_cselect_b32 s17, 0x1f600000, s17
	s_lshl_b64 s[4:5], s[4:5], 9
	s_add_u32 s4, s66, s4
	s_addc_u32 s5, s67, s5
	s_add_u32 s4, s4, s17
	s_addc_u32 s5, s5, 0
	s_mul_i32 s27, s34, 0x2c0000
	s_mul_hi_i32 s17, s34, 0x2c0000
	s_add_u32 s4, s4, s27
	s_addc_u32 s5, s5, s17
	s_movk_i32 s17, 0x1600
	s_cmp_ge_i32 s38, 22
	s_cbranch_scc1 .Lup_epi_nt
	v_lshl_add_u64 v[156:157], v[136:137], 1, s[4:5]
	v_mad_i64_i32 v[158:159], s[4:5], s17, v134, 0
	v_lshl_add_u64 v[158:159], v[158:159], 1, v[156:157]
	v_cvt_pk_bf16_f32 v108, v108, v109
	v_cvt_pk_bf16_f32 v109, v110, v111
	v_cvt_pk_bf16_f32 v110, v104, v105
	v_cvt_pk_bf16_f32 v111, v106, v107
	v_mad_i64_i32 v[104:105], s[4:5], s17, v138, 0
	v_cvt_pk_bf16_f32 v124, v124, v125
	v_cvt_pk_bf16_f32 v125, v126, v127
	v_cvt_pk_bf16_f32 v126, v120, v121
	v_cvt_pk_bf16_f32 v127, v122, v123
	global_store_dwordx4 v[158:159], v[108:111], off offset:256
	v_cvt_pk_bf16_f32 v92, v92, v93
	v_cvt_pk_bf16_f32 v93, v94, v95
	v_lshl_add_u64 v[108:109], v[104:105], 1, v[156:157]
	v_cvt_pk_bf16_f32 v94, v88, v89
	v_cvt_pk_bf16_f32 v95, v90, v91
	v_mad_i64_i32 v[88:89], s[4:5], s17, v140, 0
	global_store_dwordx4 v[158:159], v[124:127], off
	v_cvt_pk_bf16_f32 v104, v116, v117
	v_cvt_pk_bf16_f32 v105, v118, v119
	v_cvt_pk_bf16_f32 v106, v112, v113
	v_cvt_pk_bf16_f32 v107, v114, v115
	global_store_dwordx4 v[108:109], v[92:95], off offset:256
	v_cvt_pk_bf16_f32 v76, v76, v77
	v_cvt_pk_bf16_f32 v77, v78, v79
	v_lshl_add_u64 v[92:93], v[88:89], 1, v[156:157]
	v_cvt_pk_bf16_f32 v78, v72, v73
	v_cvt_pk_bf16_f32 v79, v74, v75
	v_mad_i64_i32 v[72:73], s[4:5], s17, v142, 0
	v_cvt_pk_bf16_f32 v68, v68, v69
	v_cvt_pk_bf16_f32 v69, v70, v71
	v_cvt_pk_bf16_f32 v70, v64, v65
	v_mad_i64_i32 v[64:65], s[4:5], s17, v144, 0
	global_store_dwordx4 v[108:109], v[104:107], off
	v_cvt_pk_bf16_f32 v88, v100, v101
	v_cvt_pk_bf16_f32 v89, v102, v103
	v_cvt_pk_bf16_f32 v90, v96, v97
	v_cvt_pk_bf16_f32 v91, v98, v99
	global_store_dwordx4 v[92:93], v[76:79], off offset:256
	v_cvt_pk_bf16_f32 v74, v80, v81
	v_cvt_pk_bf16_f32 v75, v82, v83
	v_lshl_add_u64 v[76:77], v[72:73], 1, v[156:157]
	v_cvt_pk_bf16_f32 v72, v84, v85
	v_cvt_pk_bf16_f32 v73, v86, v87
	v_cvt_pk_bf16_f32 v71, v66, v67
	v_lshl_add_u64 v[64:65], v[64:65], 1, v[156:157]
	v_cvt_pk_bf16_f32 v44, v44, v45
	v_cvt_pk_bf16_f32 v45, v46, v47
	v_cvt_pk_bf16_f32 v46, v40, v41
	v_cvt_pk_bf16_f32 v47, v42, v43
	v_mad_i64_i32 v[40:41], s[4:5], s17, v146, 0
	global_store_dwordx4 v[92:93], v[88:91], off
	global_store_dwordx4 v[76:77], v[72:75], off
	global_store_dwordx4 v[76:77], v[68:71], off offset:256
	v_cvt_pk_bf16_f32 v60, v60, v61
	v_cvt_pk_bf16_f32 v61, v62, v63
	v_cvt_pk_bf16_f32 v62, v56, v57
	v_cvt_pk_bf16_f32 v63, v58, v59
	global_store_dwordx4 v[64:65], v[44:47], off offset:256
	v_cvt_pk_bf16_f32 v28, v28, v29
	v_cvt_pk_bf16_f32 v29, v30, v31
	v_lshl_add_u64 v[44:45], v[40:41], 1, v[156:157]
	v_cvt_pk_bf16_f32 v30, v24, v25
	v_cvt_pk_bf16_f32 v31, v26, v27
	v_mad_i64_i32 v[24:25], s[4:5], s17, v148, 0
	global_store_dwordx4 v[64:65], v[60:63], off
	v_cvt_pk_bf16_f32 v40, v52, v53
	v_cvt_pk_bf16_f32 v41, v54, v55
	v_cvt_pk_bf16_f32 v42, v48, v49
	v_cvt_pk_bf16_f32 v43, v50, v51
	global_store_dwordx4 v[44:45], v[28:31], off offset:256
	v_cvt_pk_bf16_f32 v12, v12, v13
	v_cvt_pk_bf16_f32 v13, v14, v15
	v_lshl_add_u64 v[28:29], v[24:25], 1, v[156:157]
	v_cvt_pk_bf16_f32 v14, v8, v9
	v_cvt_pk_bf16_f32 v15, v10, v11
	v_mad_i64_i32 v[8:9], s[4:5], s17, v150, 0
	global_store_dwordx4 v[44:45], v[40:43], off
	v_cvt_pk_bf16_f32 v24, v36, v37
	v_cvt_pk_bf16_f32 v25, v38, v39
	v_cvt_pk_bf16_f32 v26, v32, v33
	v_cvt_pk_bf16_f32 v27, v34, v35
	global_store_dwordx4 v[28:29], v[12:15], off offset:256
	v_cvt_pk_bf16_f32 v10, v16, v17
	v_cvt_pk_bf16_f32 v11, v18, v19
	v_lshl_add_u64 v[12:13], v[8:9], 1, v[156:157]
	v_cvt_pk_bf16_f32 v8, v20, v21
	v_cvt_pk_bf16_f32 v9, v22, v23
	v_cvt_pk_bf16_f32 v4, v4, v5
	v_cvt_pk_bf16_f32 v5, v6, v7
	v_cvt_pk_bf16_f32 v6, v0, v1
	v_cvt_pk_bf16_f32 v7, v2, v3
	s_and_b64 vcc, exec, s[36:37]
	s_mov_b32 s38, s42
	s_mov_b32 s34, s44
	s_mov_b64 s[50:51], s[48:49]
	s_mov_b64 s[40:41], s[46:47]
	global_store_dwordx4 v[28:29], v[24:27], off
	global_store_dwordx4 v[12:13], v[8:11], off
	global_store_dwordx4 v[12:13], v[4:7], off offset:256
	s_cbranch_vccz .LBB0_1117
	s_branch .Lup_epi_done
; __device__ __forceinline__ unsigned cvt_pk_bf16(float lo, float hi) { const f32x2 v = {lo, hi}; return __builtin_bit_cast(unsigned, __builtin_convertvector(v, bf16x2_t)); }
; #define PG8_WAIT_V(n) asm volatile("s_waitcnt vmcnt(" #n ")" ::: "memory")
; #define PG8_BAR __builtin_amdgcn_s_barrier()
;     template <class Sched> __device__ __forceinline__ void operator()(const f32x4 (&acc)[2][2][4][2], const Unit& u, const Sched& S, int wr, int wc, int fr, int fq) const {
;     ...
;         if (kind == 0) {
;             bf16_t* base = (bf16_t*)uo;
; #pragma unroll
;             for (int ai = 0; ai < 2; ++ai)
; #pragma unroll
;                 for (int m = 0; m < 4; ++m) { bf16_t* rowp = base + (size_t)(rl0 + ai * HALF + m * 16) * ldo + cl0;
; #pragma unroll
;                     for (int bj = 0; bj < 2; ++bj) { const f32x4 v0 = acc[ai][bj][m][0], v1 = acc[ai][bj][m][1];
;                         u32x4 w; w.x = cvt_pk_bf16(v0[0], v0[1]); w.y = cvt_pk_bf16(v0[2], v0[3]); w.z = cvt_pk_bf16(v1[0], v1[1]); w.w = cvt_pk_bf16(v1[2], v1[3]);
;                         *(u32x4*)(rowp + bj * HALF) = w; } }
; template <class Epi, class Sched, bool ALIGN_EPI>
; __device__ __forceinline__ void gemm_phase(LAS unsigned char* lds, const int wid, const int lda_, const int ldb_, const int K_, const Sched& S, const Epi& E) {
;     ...
;         cur = nxt; cA = nA; cB = nB; ++ui;
;         if constexpr (ALIGN_EPI) { if (wr == 1) PG8_BAR; }
;     }
;     PG8_WAIT_V(0);
;     if constexpr (!ALIGN_EPI) { if (wr == 0) PG8_BAR; }
;     PG8_BAR;
.Lup_epi_nt:
	v_lshl_add_u64 v[156:157], v[136:137], 1, s[4:5]
	v_mad_i64_i32 v[158:159], s[4:5], s17, v134, 0
	v_lshl_add_u64 v[158:159], v[158:159], 1, v[156:157]
	v_cvt_pk_bf16_f32 v108, v108, v109
	v_cvt_pk_bf16_f32 v109, v110, v111
	v_cvt_pk_bf16_f32 v110, v104, v105
	v_cvt_pk_bf16_f32 v111, v106, v107
	v_mad_i64_i32 v[104:105], s[4:5], s17, v138, 0
	v_cvt_pk_bf16_f32 v124, v124, v125
	v_cvt_pk_bf16_f32 v125, v126, v127
	v_cvt_pk_bf16_f32 v126, v120, v121
	v_cvt_pk_bf16_f32 v127, v122, v123
	global_store_dwordx4 v[158:159], v[108:111], off offset:256 nt
	v_cvt_pk_bf16_f32 v92, v92, v93
	v_cvt_pk_bf16_f32 v93, v94, v95
	v_lshl_add_u64 v[108:109], v[104:105], 1, v[156:157]
	v_cvt_pk_bf16_f32 v94, v88, v89
	v_cvt_pk_bf16_f32 v95, v90, v91
	v_mad_i64_i32 v[88:89], s[4:5], s17, v140, 0
	global_store_dwordx4 v[158:159], v[124:127], off nt
	v_cvt_pk_bf16_f32 v104, v116, v117
	v_cvt_pk_bf16_f32 v105, v118, v119
	v_cvt_pk_bf16_f32 v106, v112, v113
	v_cvt_pk_bf16_f32 v107, v114, v115
	global_store_dwordx4 v[108:109], v[92:95], off offset:256 nt
	v_cvt_pk_bf16_f32 v76, v76, v77
	v_cvt_pk_bf16_f32 v77, v78, v79
	v_lshl_add_u64 v[92:93], v[88:89], 1, v[156:157]
	v_cvt_pk_bf16_f32 v78, v72, v73
	v_cvt_pk_bf16_f32 v79, v74, v75
	v_mad_i64_i32 v[72:73], s[4:5], s17, v142, 0
	v_cvt_pk_bf16_f32 v68, v68, v69
	v_cvt_pk_bf16_f32 v69, v70, v71
	v_cvt_pk_bf16_f32 v70, v64, v65
	v_mad_i64_i32 v[64:65], s[4:5], s17, v144, 0
	global_store_dwordx4 v[108:109], v[104:107], off nt
	v_cvt_pk_bf16_f32 v88, v100, v101
	v_cvt_pk_bf16_f32 v89, v102, v103
	v_cvt_pk_bf16_f32 v90, v96, v97
	v_cvt_pk_bf16_f32 v91, v98, v99
	global_store_dwordx4 v[92:93], v[76:79], off offset:256 nt
	v_cvt_pk_bf16_f32 v74, v80, v81
	v_cvt_pk_bf16_f32 v75, v82, v83
	v_lshl_add_u64 v[76:77], v[72:73], 1, v[156:157]
	v_cvt_pk_bf16_f32 v72, v84, v85
	v_cvt_pk_bf16_f32 v73, v86, v87
	v_cvt_pk_bf16_f32 v71, v66, v67
	v_lshl_add_u64 v[64:65], v[64:65], 1, v[156:157]
	v_cvt_pk_bf16_f32 v44, v44, v45
	v_cvt_pk_bf16_f32 v45, v46, v47
	v_cvt_pk_bf16_f32 v46, v40, v41
	v_cvt_pk_bf16_f32 v47, v42, v43
	v_mad_i64_i32 v[40:41], s[4:5], s17, v146, 0
	global_store_dwordx4 v[92:93], v[88:91], off nt
	global_store_dwordx4 v[76:77], v[72:75], off nt
	global_store_dwordx4 v[76:77], v[68:71], off offset:256 nt
	v_cvt_pk_bf16_f32 v60, v60, v61
	v_cvt_pk_bf16_f32 v61, v62, v63
	v_cvt_pk_bf16_f32 v62, v56, v57
	v_cvt_pk_bf16_f32 v63, v58, v59
	global_store_dwordx4 v[64:65], v[44:47], off offset:256 nt
	v_cvt_pk_bf16_f32 v28, v28, v29
	v_cvt_pk_bf16_f32 v29, v30, v31
	v_lshl_add_u64 v[44:45], v[40:41], 1, v[156:157]
	v_cvt_pk_bf16_f32 v30, v24, v25
	v_cvt_pk_bf16_f32 v31, v26, v27
	v_mad_i64_i32 v[24:25], s[4:5], s17, v148, 0
	global_store_dwordx4 v[64:65], v[60:63], off nt
	v_cvt_pk_bf16_f32 v40, v52, v53
	v_cvt_pk_bf16_f32 v41, v54, v55
	v_cvt_pk_bf16_f32 v42, v48, v49
	v_cvt_pk_bf16_f32 v43, v50, v51
	global_store_dwordx4 v[44:45], v[28:31], off offset:256 nt
	v_cvt_pk_bf16_f32 v12, v12, v13
	v_cvt_pk_bf16_f32 v13, v14, v15
	v_lshl_add_u64 v[28:29], v[24:25], 1, v[156:157]
	v_cvt_pk_bf16_f32 v14, v8, v9
	v_cvt_pk_bf16_f32 v15, v10, v11
	v_mad_i64_i32 v[8:9], s[4:5], s17, v150, 0
	global_store_dwordx4 v[44:45], v[40:43], off nt
	v_cvt_pk_bf16_f32 v24, v36, v37
	v_cvt_pk_bf16_f32 v25, v38, v39
	v_cvt_pk_bf16_f32 v26, v32, v33
	v_cvt_pk_bf16_f32 v27, v34, v35
	global_store_dwordx4 v[28:29], v[12:15], off offset:256 nt
	v_cvt_pk_bf16_f32 v10, v16, v17
	v_cvt_pk_bf16_f32 v11, v18, v19
	v_lshl_add_u64 v[12:13], v[8:9], 1, v[156:157]
	v_cvt_pk_bf16_f32 v8, v20, v21
	v_cvt_pk_bf16_f32 v9, v22, v23
	v_cvt_pk_bf16_f32 v4, v4, v5
	v_cvt_pk_bf16_f32 v5, v6, v7
	v_cvt_pk_bf16_f32 v6, v0, v1
	v_cvt_pk_bf16_f32 v7, v2, v3
	s_and_b64 vcc, exec, s[36:37]
	s_mov_b32 s38, s42
	s_mov_b32 s34, s44
	s_mov_b64 s[50:51], s[48:49]
	s_mov_b64 s[40:41], s[46:47]
	global_store_dwordx4 v[28:29], v[24:27], off nt
	global_store_dwordx4 v[12:13], v[8:11], off nt
	global_store_dwordx4 v[12:13], v[4:7], off offset:256 nt
	s_cbranch_vccz .LBB0_1117
	s_branch .Lup_epi_done
.Lup_epi_done:
	v_readlane_b32 s4, v253, 1
	s_waitcnt vmcnt(0)
	v_readlane_b32 s5, v253, 2
	s_andn2_b64 vcc, exec, s[4:5]
	s_cbranch_vccnz .LBB0_1124
	s_barrier
